# v16: v12 plus online-softmax rescale test (alpha != 1 ballot + branch + rare O rescale) moved off the serial chain to after the exp/cvt block in all six attention sub-tile bodies
# speedup vs baseline: 1.0073x; 1.0072x over previous
; __device__ __forceinline__ void att_softmax(f32x16& s, float sc, float& m, float& l, f32x16 (&o)[4], bf16x8& pf0, bf16x8& pf1) {
;     ...
;     const float alpha = __builtin_amdgcn_exp2f(m - msafe);
;     m = mnew;
;     float rs0 = 0.f, rs1 = 0.f;
; #pragma unroll
;     for (int i = 0; i < 16; i += 2) { s[i] = __builtin_amdgcn_exp2f(s[i] * sc - msafe); s[i + 1] = __builtin_amdgcn_exp2f(s[i + 1] * sc - msafe); rs0 += s[i]; rs1 += s[i + 1]; }
;     l = l * alpha + (rs0 + rs1);
;     if (__builtin_amdgcn_ballot_w64(alpha != 1.0f) != 0ull) {
; #pragma unroll
;         for (int db = 0; db < 4; ++db) o[db] = o[db] * alpha; }
;     v4u pw0, pw1;
;     pw0.x = cvtpk(s[0], s[1]); pw0.y = cvtpk(s[2], s[3]); pw0.z = cvtpk(s[4], s[5]); pw0.w = cvtpk(s[6], s[7]);
;     pw1.x = cvtpk(s[8], s[9]); pw1.y = cvtpk(s[10], s[11]); pw1.z = cvtpk(s[12], s[13]); pw1.w = cvtpk(s[14], s[15]);
;     pf0 = __builtin_bit_cast(bf16x8, pw0); pf1 = __builtin_bit_cast(bf16x8, pw1);
.LBB0_118:
	v_fma_f32 v66, v66, s5, -v234
	v_fma_f32 v67, v67, s5, -v234
	v_exp_f32_e32 v66, v66
	v_exp_f32_e32 v67, v67
	v_fma_f32 v68, v68, s5, -v234
	v_fma_f32 v69, v69, s5, -v234
	v_exp_f32_e32 v68, v68
	v_exp_f32_e32 v69, v69
	v_fma_f32 v70, v70, s5, -v234
	v_fma_f32 v71, v71, s5, -v234
	v_exp_f32_e32 v70, v70
	v_exp_f32_e32 v71, v71
	v_fma_f32 v72, v72, s5, -v234
	v_fma_f32 v73, v73, s5, -v234
	v_exp_f32_e32 v72, v72
	v_exp_f32_e32 v73, v73
	v_fma_f32 v74, v74, s5, -v234
	v_fma_f32 v75, v75, s5, -v234
	v_add_f32_e32 v200, 0, v66
	v_add_f32_e32 v201, 0, v67
	v_exp_f32_e32 v74, v74
	v_exp_f32_e32 v75, v75
	v_fma_f32 v76, v76, s5, -v234
	v_fma_f32 v77, v77, s5, -v234
	v_add_f32_e32 v200, v68, v200
	v_add_f32_e32 v201, v69, v201
	v_exp_f32_e32 v76, v76
	v_exp_f32_e32 v77, v77
	v_fma_f32 v78, v78, s5, -v234
	v_fma_f32 v79, v79, s5, -v234
	v_add_f32_e32 v200, v70, v200
	v_add_f32_e32 v201, v71, v201
	v_exp_f32_e32 v78, v78
	v_exp_f32_e32 v79, v79
	v_fma_f32 v80, v80, s5, -v234
	v_fma_f32 v81, v81, s5, -v234
	v_add_f32_e32 v200, v72, v200
	v_add_f32_e32 v201, v73, v201
	v_exp_f32_e32 v80, v80
	v_exp_f32_e32 v81, v81
	v_add_f32_e32 v200, v74, v200
	v_add_f32_e32 v201, v75, v201
	v_add_f32_e32 v200, v76, v200
	v_add_f32_e32 v201, v77, v201
	v_add_f32_e32 v200, v78, v200
	v_add_f32_e32 v201, v79, v201
	v_add_f32_e32 v200, v80, v200
	v_add_f32_e32 v201, v81, v201
	v_add_f32_e32 v234, v200, v201
	v_fmac_f32_e32 v234, v233, v224
	s_cmp_ge_i32 s85, s67
	v_cvt_pk_bf16_f32 v66, v66, v67
	v_cvt_pk_bf16_f32 v67, v68, v69
	v_cvt_pk_bf16_f32 v68, v70, v71
	v_cvt_pk_bf16_f32 v69, v72, v73
	v_cvt_pk_bf16_f32 v70, v74, v75
	v_cvt_pk_bf16_f32 v71, v76, v77
	v_cvt_pk_bf16_f32 v72, v78, v79
	v_cvt_pk_bf16_f32 v73, v80, v81
	v_cmp_neq_f32_e32 vcc, 1.0, v224
	s_cbranch_vccz .Lresc_skip_1
	v_pk_mul_f32 v[64:65], v[64:65], v[224:225] op_sel_hi:[1,0]
	v_pk_mul_f32 v[62:63], v[62:63], v[224:225] op_sel_hi:[1,0]
	v_pk_mul_f32 v[60:61], v[60:61], v[224:225] op_sel_hi:[1,0]
	v_pk_mul_f32 v[58:59], v[58:59], v[224:225] op_sel_hi:[1,0]
	v_pk_mul_f32 v[56:57], v[56:57], v[224:225] op_sel_hi:[1,0]
	v_pk_mul_f32 v[54:55], v[54:55], v[224:225] op_sel_hi:[1,0]
	v_pk_mul_f32 v[52:53], v[52:53], v[224:225] op_sel_hi:[1,0]
	v_pk_mul_f32 v[50:51], v[50:51], v[224:225] op_sel_hi:[1,0]
	v_pk_mul_f32 v[48:49], v[48:49], v[224:225] op_sel_hi:[1,0]
	v_pk_mul_f32 v[46:47], v[46:47], v[224:225] op_sel_hi:[1,0]
	v_pk_mul_f32 v[44:45], v[44:45], v[224:225] op_sel_hi:[1,0]
	v_pk_mul_f32 v[42:43], v[42:43], v[224:225] op_sel_hi:[1,0]
	v_pk_mul_f32 v[40:41], v[40:41], v[224:225] op_sel_hi:[1,0]
	v_pk_mul_f32 v[38:39], v[38:39], v[224:225] op_sel_hi:[1,0]
	v_pk_mul_f32 v[36:37], v[36:37], v[224:225] op_sel_hi:[1,0]
	v_pk_mul_f32 v[34:35], v[34:35], v[224:225] op_sel_hi:[1,0]
	v_pk_mul_f32 v[32:33], v[32:33], v[224:225] op_sel_hi:[1,0]
	v_pk_mul_f32 v[30:31], v[30:31], v[224:225] op_sel_hi:[1,0]
	v_pk_mul_f32 v[28:29], v[28:29], v[224:225] op_sel_hi:[1,0]
	v_pk_mul_f32 v[26:27], v[26:27], v[224:225] op_sel_hi:[1,0]
	v_pk_mul_f32 v[24:25], v[24:25], v[224:225] op_sel_hi:[1,0]
	v_pk_mul_f32 v[22:23], v[22:23], v[224:225] op_sel_hi:[1,0]
	v_pk_mul_f32 v[20:21], v[20:21], v[224:225] op_sel_hi:[1,0]
	v_pk_mul_f32 v[18:19], v[18:19], v[224:225] op_sel_hi:[1,0]
	v_pk_mul_f32 v[16:17], v[16:17], v[224:225] op_sel_hi:[1,0]
	v_pk_mul_f32 v[14:15], v[14:15], v[224:225] op_sel_hi:[1,0]
	v_pk_mul_f32 v[12:13], v[12:13], v[224:225] op_sel_hi:[1,0]
	v_pk_mul_f32 v[10:11], v[10:11], v[224:225] op_sel_hi:[1,0]
	v_pk_mul_f32 v[8:9], v[8:9], v[224:225] op_sel_hi:[1,0]
	v_pk_mul_f32 v[6:7], v[6:7], v[224:225] op_sel_hi:[1,0]
	v_pk_mul_f32 v[4:5], v[4:5], v[224:225] op_sel_hi:[1,0]
	v_pk_mul_f32 v[2:3], v[2:3], v[224:225] op_sel_hi:[1,0]
	s_nop 1
; #define LAS __attribute__((address_space(3)))
; #define MFMA32(a, b, c) __builtin_amdgcn_mfma_f32_32x32x16_bf16((a), (b), (c), 0, 0, 0)
; template <int NC1, int NC2, class Ctl> ...
;     ...
;             for (int c = 0; c < NC; ++c) kf[c] = *(const LAS bf16x8*)(kbase + first * 32 * Gm::KSTRIDE + c * 32);
; #pragma unroll
;             for (int sb = 0; sb < 2; ++sb) {
;                 if (!(sb ? nB : nA)) continue;
;                 if (!KPRE && sb == 1 && nA) {
; #pragma unroll
;                     for (int c = 0; c < NC; ++c) kf[c] = *(const LAS bf16x8*)(kbase + 32 * Gm::KSTRIDE + c * 32); }
;                 f32x16 s;
; #pragma unroll
;                 for (int i = 0; i < 16; ++i) s[i] = 0.f;
; #pragma unroll
;                 for (int c = 0; c < NC; ++c) s = MFMA32(kf[c], qf[c], s);
;                 __builtin_amdgcn_sched_barrier(0);
;                 v4u av[8];
; #pragma unroll
;                 for (int s_ = 0; s_ < 2; ++s_)
; #pragma unroll
;                     for (int db = 0; db < 4; ++db) { const LAS v2u* p0 = (const LAS v2u*)(vbase + sb * 64 + db * 32 * 136 + s_ * 32); const v2u al = p0[0], ah = p0[2]; av[s_ * 4 + db] = (v4u){al.x, al.y, ah.x, ah.y}; }
;                 if (KPRE && sb == 0 && nB) {
; #pragma unroll
;                     for (int c = 0; c < NC; ++c) kf[c] = *(const LAS bf16x8*)(kbase + 32 * Gm::KSTRIDE + c * 32); }
;                 __builtin_amdgcn_sched_barrier(0);
;                 bf16x8 pa0, pa1;
;                 ctl.mask(s, sb ? kvB : kvA); att_softmax(s, sc, m, l, o, pa0, pa1);
;                 __builtin_amdgcn_sched_barrier(0);
; #pragma unroll
;                 for (int s_ = 0; s_ < 2; ++s_)
; #pragma unroll
;                     for (int db = 0; db < 4; ++db) o[db] = MFMA32(__builtin_bit_cast(bf16x8, av[s_ * 4 + db]), s_ ? pa1 : pa0, o[db]);
.Lresc_skip_1:
	s_waitcnt lgkmcnt(7)
	v_mfma_f32_32x32x16_bf16 v[50:65], v[166:169], v[66:69], v[50:65]
	s_waitcnt lgkmcnt(5)
	v_mfma_f32_32x32x16_bf16 v[34:49], v[170:173], v[66:69], v[34:49]
	s_waitcnt lgkmcnt(4)
	v_mfma_f32_32x32x16_bf16 v[18:33], v[178:181], v[66:69], v[18:33]
	s_waitcnt lgkmcnt(3)
	v_mfma_f32_32x32x16_bf16 v[2:17], v[174:177], v[66:69], v[2:17]
	v_mfma_f32_32x32x16_bf16 v[50:65], v[150:153], v[70:73], v[50:65]
	s_waitcnt lgkmcnt(2)
	v_mfma_f32_32x32x16_bf16 v[34:49], v[162:165], v[70:73], v[34:49]
	s_waitcnt lgkmcnt(1)
	v_mfma_f32_32x32x16_bf16 v[18:33], v[158:161], v[70:73], v[18:33]
	s_waitcnt lgkmcnt(0)
	v_mfma_f32_32x32x16_bf16 v[2:17], v[154:157], v[70:73], v[2:17]
	s_cbranch_scc1 .LBB0_126
	ds_read_b128 v[66:69], v235 offset:12800
	ds_read_b128 v[150:153], v235 offset:12832
	ds_read_b128 v[154:157], v235 offset:12864
	ds_read_b128 v[158:161], v235 offset:12896
	ds_read_b128 v[162:165], v235 offset:12928
	ds_read_b128 v[166:169], v235 offset:12960
	ds_read_b128 v[170:173], v235 offset:12992
	ds_read_b128 v[174:177], v235 offset:13024
	ds_read_b128 v[178:181], v235 offset:13056
	ds_read_b128 v[200:203], v235 offset:13088
	ds_read_b128 v[208:211], v235 offset:13120
	ds_read_b128 v[250:253], v235 offset:13152
	s_waitcnt lgkmcnt(11)
	v_mfma_f32_32x32x16_bf16 v[66:81], v[66:69], v[82:85], 0
	s_waitcnt lgkmcnt(10)
	v_mfma_f32_32x32x16_bf16 v[66:81], v[150:153], v[86:89], v[66:81]
	s_waitcnt lgkmcnt(9)
	v_mfma_f32_32x32x16_bf16 v[66:81], v[154:157], v[90:93], v[66:81]
	s_waitcnt lgkmcnt(8)
	v_mfma_f32_32x32x16_bf16 v[66:81], v[158:161], v[94:97], v[66:81]
	s_waitcnt lgkmcnt(7)
	v_mfma_f32_32x32x16_bf16 v[66:81], v[162:165], v[98:101], v[66:81]
	s_waitcnt lgkmcnt(6)
	v_mfma_f32_32x32x16_bf16 v[66:81], v[166:169], v[102:105], v[66:81]
	s_waitcnt lgkmcnt(5)
	v_mfma_f32_32x32x16_bf16 v[66:81], v[170:173], v[106:109], v[66:81]
	ds_read2_b64 v[170:173], v246 offset0:136 offset1:138
	s_waitcnt lgkmcnt(5)
	v_mfma_f32_32x32x16_bf16 v[66:81], v[174:177], v[110:113], v[66:81]
	s_waitcnt lgkmcnt(4)
	v_mfma_f32_32x32x16_bf16 v[66:81], v[178:181], v[126:129], v[66:81]
	ds_read2_b64 v[154:157], v246 offset0:140 offset1:142
	ds_read2_b64 v[178:181], v245 offset0:168 offset1:170
	ds_read2_b64 v[174:177], v247 offset0:200 offset1:202
	ds_read2_b64 v[166:169], v248 offset0:232 offset1:234
	ds_read2_b64 v[162:165], v245 offset0:172 offset1:174
	ds_read2_b64 v[158:161], v247 offset0:204 offset1:206
	ds_read2_b64 v[150:153], v248 offset0:236 offset1:238
	s_waitcnt lgkmcnt(10)
	v_mfma_f32_32x32x16_bf16 v[66:81], v[200:203], v[142:145], v[66:81]
	s_waitcnt lgkmcnt(9)
	v_mfma_f32_32x32x16_bf16 v[66:81], v[208:211], v[130:133], v[66:81]
	s_waitcnt lgkmcnt(8)
	v_mfma_f32_32x32x16_bf16 v[66:81], v[250:253], v[146:149], v[66:81]
	s_cmp_lg_u32 s79, s85
	s_cbranch_scc1 .LBB0_123
	s_nop 9
	v_cndmask_b32_e64 v200, v66, v241, s[12:13]
	v_cndmask_b32_e64 v67, v241, v67, s[14:15]
	v_cndmask_b32_e64 v66, v200, v66, s[14:15]
	v_cndmask_b32_e64 v68, v68, v241, s[16:17]
	v_cndmask_b32_e64 v69, v69, v241, s[18:19]
	v_cndmask_b32_e64 v70, v70, v241, s[20:21]
	v_cndmask_b32_e64 v71, v71, v241, s[22:23]
	v_cndmask_b32_e64 v72, v72, v241, s[24:25]
	v_cndmask_b32_e64 v73, v73, v241, s[26:27]
	v_cndmask_b32_e64 v74, v74, v241, s[28:29]
	v_cndmask_b32_e64 v75, v75, v241, s[30:31]
	v_cndmask_b32_e64 v76, v76, v241, s[34:35]
	v_cndmask_b32_e64 v77, v77, v241, s[36:37]
	v_cndmask_b32_e64 v78, v78, v241, s[38:39]
	v_cndmask_b32_e64 v79, v79, v241, s[40:41]
	v_cndmask_b32_e64 v80, v80, v241, s[42:43]
	s_and_saveexec_b64 vcc, s[44:45]
	v_mov_b32_e32 v81, s51
	s_or_b64 exec, exec, vcc

; #define MFMA32(a, b, c) __builtin_amdgcn_mfma_f32_32x32x16_bf16((a), (b), (c), 0, 0, 0)
; __device__ __forceinline__ void att_softmax(f32x16& s, float sc, float& m, float& l, f32x16 (&o)[4], bf16x8& pf0, bf16x8& pf1) {
;     ...
;     const float alpha = __builtin_amdgcn_exp2f(m - msafe);
;     m = mnew;
;     float rs0 = 0.f, rs1 = 0.f;
; #pragma unroll
;     for (int i = 0; i < 16; i += 2) { s[i] = __builtin_amdgcn_exp2f(s[i] * sc - msafe); s[i + 1] = __builtin_amdgcn_exp2f(s[i + 1] * sc - msafe); rs0 += s[i]; rs1 += s[i + 1]; }
;     l = l * alpha + (rs0 + rs1);
;     if (__builtin_amdgcn_ballot_w64(alpha != 1.0f) != 0ull) {
; #pragma unroll
;         for (int db = 0; db < 4; ++db) o[db] = o[db] * alpha; }
;     v4u pw0, pw1;
;     pw0.x = cvtpk(s[0], s[1]); pw0.y = cvtpk(s[2], s[3]); pw0.z = cvtpk(s[4], s[5]); pw0.w = cvtpk(s[6], s[7]);
;     pw1.x = cvtpk(s[8], s[9]); pw1.y = cvtpk(s[10], s[11]); pw1.z = cvtpk(s[12], s[13]); pw1.w = cvtpk(s[14], s[15]);
;     pf0 = __builtin_bit_cast(bf16x8, pw0); pf1 = __builtin_bit_cast(bf16x8, pw1);
; template <int NC1, int NC2, class Ctl> ...
;     ...
; #pragma unroll
;                 for (int s_ = 0; s_ < 2; ++s_)
; #pragma unroll
;                     for (int db = 0; db < 4; ++db) o[db] = MFMA32(__builtin_bit_cast(bf16x8, av[s_ * 4 + db]), s_ ? pa1 : pa0, o[db]);
.LBB0_125:
	v_fma_f32 v66, v66, s5, -v233
	v_fma_f32 v67, v67, s5, -v233
	v_exp_f32_e32 v66, v66
	v_exp_f32_e32 v67, v67
	v_fma_f32 v68, v68, s5, -v233
	v_fma_f32 v69, v69, s5, -v233
	v_exp_f32_e32 v68, v68
	v_exp_f32_e32 v69, v69
	v_fma_f32 v70, v70, s5, -v233
	v_fma_f32 v71, v71, s5, -v233
	v_exp_f32_e32 v70, v70
	v_exp_f32_e32 v71, v71
	v_fma_f32 v72, v72, s5, -v233
	v_fma_f32 v73, v73, s5, -v233
	v_exp_f32_e32 v72, v72
	v_exp_f32_e32 v73, v73
	v_fma_f32 v74, v74, s5, -v233
	v_fma_f32 v75, v75, s5, -v233
	v_add_f32_e32 v200, 0, v66
	v_add_f32_e32 v201, 0, v67
	v_exp_f32_e32 v74, v74
	v_exp_f32_e32 v75, v75
	v_fma_f32 v76, v76, s5, -v233
	v_fma_f32 v77, v77, s5, -v233
	v_add_f32_e32 v200, v68, v200
	v_add_f32_e32 v201, v69, v201
	v_exp_f32_e32 v76, v76
	v_exp_f32_e32 v77, v77
	v_fma_f32 v78, v78, s5, -v233
	v_fma_f32 v79, v79, s5, -v233
	v_add_f32_e32 v200, v70, v200
	v_add_f32_e32 v201, v71, v201
	v_exp_f32_e32 v78, v78
	v_exp_f32_e32 v79, v79
	v_fma_f32 v80, v80, s5, -v233
	v_fma_f32 v81, v81, s5, -v233
	v_add_f32_e32 v200, v72, v200
	v_add_f32_e32 v201, v73, v201
	v_exp_f32_e32 v80, v80
	v_exp_f32_e32 v81, v81
	v_add_f32_e32 v200, v74, v200
	v_add_f32_e32 v201, v75, v201
	v_add_f32_e32 v200, v76, v200
	v_add_f32_e32 v201, v77, v201
	v_add_f32_e32 v200, v78, v200
	v_add_f32_e32 v201, v79, v201
	v_add_f32_e32 v200, v80, v200
	v_add_f32_e32 v201, v81, v201
	v_add_f32_e32 v200, v200, v201
	v_fmac_f32_e32 v200, v234, v224
	v_cvt_pk_bf16_f32 v66, v66, v67
	v_cvt_pk_bf16_f32 v67, v68, v69
	v_cvt_pk_bf16_f32 v68, v70, v71
	v_cvt_pk_bf16_f32 v69, v72, v73
	v_cvt_pk_bf16_f32 v70, v74, v75
	v_cvt_pk_bf16_f32 v71, v76, v77
	v_cvt_pk_bf16_f32 v72, v78, v79
	v_cvt_pk_bf16_f32 v73, v80, v81
	v_cmp_neq_f32_e32 vcc, 1.0, v224
	s_cbranch_vccz .Lresc_skip_2
	v_pk_mul_f32 v[64:65], v[64:65], v[224:225] op_sel_hi:[1,0]
	v_pk_mul_f32 v[62:63], v[62:63], v[224:225] op_sel_hi:[1,0]
	v_pk_mul_f32 v[60:61], v[60:61], v[224:225] op_sel_hi:[1,0]
	v_pk_mul_f32 v[58:59], v[58:59], v[224:225] op_sel_hi:[1,0]
	v_pk_mul_f32 v[56:57], v[56:57], v[224:225] op_sel_hi:[1,0]
	v_pk_mul_f32 v[54:55], v[54:55], v[224:225] op_sel_hi:[1,0]
	v_pk_mul_f32 v[52:53], v[52:53], v[224:225] op_sel_hi:[1,0]
	v_pk_mul_f32 v[50:51], v[50:51], v[224:225] op_sel_hi:[1,0]
	v_pk_mul_f32 v[48:49], v[48:49], v[224:225] op_sel_hi:[1,0]
	v_pk_mul_f32 v[46:47], v[46:47], v[224:225] op_sel_hi:[1,0]
	v_pk_mul_f32 v[44:45], v[44:45], v[224:225] op_sel_hi:[1,0]
	v_pk_mul_f32 v[42:43], v[42:43], v[224:225] op_sel_hi:[1,0]
	v_pk_mul_f32 v[40:41], v[40:41], v[224:225] op_sel_hi:[1,0]
	v_pk_mul_f32 v[38:39], v[38:39], v[224:225] op_sel_hi:[1,0]
	v_pk_mul_f32 v[36:37], v[36:37], v[224:225] op_sel_hi:[1,0]
	v_pk_mul_f32 v[34:35], v[34:35], v[224:225] op_sel_hi:[1,0]
	v_pk_mul_f32 v[32:33], v[32:33], v[224:225] op_sel_hi:[1,0]
	v_pk_mul_f32 v[30:31], v[30:31], v[224:225] op_sel_hi:[1,0]
	v_pk_mul_f32 v[28:29], v[28:29], v[224:225] op_sel_hi:[1,0]
	v_pk_mul_f32 v[26:27], v[26:27], v[224:225] op_sel_hi:[1,0]
	v_pk_mul_f32 v[24:25], v[24:25], v[224:225] op_sel_hi:[1,0]
	v_pk_mul_f32 v[22:23], v[22:23], v[224:225] op_sel_hi:[1,0]
	v_pk_mul_f32 v[20:21], v[20:21], v[224:225] op_sel_hi:[1,0]
	v_pk_mul_f32 v[18:19], v[18:19], v[224:225] op_sel_hi:[1,0]
	v_pk_mul_f32 v[16:17], v[16:17], v[224:225] op_sel_hi:[1,0]
	v_pk_mul_f32 v[14:15], v[14:15], v[224:225] op_sel_hi:[1,0]
	v_pk_mul_f32 v[12:13], v[12:13], v[224:225] op_sel_hi:[1,0]
	v_pk_mul_f32 v[10:11], v[10:11], v[224:225] op_sel_hi:[1,0]
	v_pk_mul_f32 v[8:9], v[8:9], v[224:225] op_sel_hi:[1,0]
	v_pk_mul_f32 v[6:7], v[6:7], v[224:225] op_sel_hi:[1,0]
	v_pk_mul_f32 v[4:5], v[4:5], v[224:225] op_sel_hi:[1,0]
	v_pk_mul_f32 v[2:3], v[2:3], v[224:225] op_sel_hi:[1,0]
	s_nop 1
.Lresc_skip_2:
	s_waitcnt lgkmcnt(7)
	v_mfma_f32_32x32x16_bf16 v[50:65], v[170:173], v[66:69], v[50:65]
	s_waitcnt lgkmcnt(5)
	v_mfma_f32_32x32x16_bf16 v[34:49], v[178:181], v[66:69], v[34:49]
	s_waitcnt lgkmcnt(4)
	v_mfma_f32_32x32x16_bf16 v[18:33], v[174:177], v[66:69], v[18:33]
	s_waitcnt lgkmcnt(3)
	v_mfma_f32_32x32x16_bf16 v[2:17], v[166:169], v[66:69], v[2:17]
	v_mfma_f32_32x32x16_bf16 v[50:65], v[154:157], v[70:73], v[50:65]
	s_waitcnt lgkmcnt(2)
	v_mfma_f32_32x32x16_bf16 v[34:49], v[162:165], v[70:73], v[34:49]
	s_waitcnt lgkmcnt(1)
	v_mfma_f32_32x32x16_bf16 v[18:33], v[158:161], v[70:73], v[18:33]
	s_waitcnt lgkmcnt(0)
	v_mfma_f32_32x32x16_bf16 v[2:17], v[150:153], v[70:73], v[2:17]
	v_mov_b32_e32 v234, v200
	v_mov_b32_e32 v233, v234
	s_andn2_b64 vcc, exec, s[96:97]
	s_cbranch_vccz .LBB0_108
	s_branch .LBB0_109

; #define MFMA32(a, b, c) __builtin_amdgcn_mfma_f32_32x32x16_bf16((a), (b), (c), 0, 0, 0)
; __device__ __forceinline__ void att_softmax(f32x16& s, float sc, float& m, float& l, f32x16 (&o)[4], bf16x8& pf0, bf16x8& pf1) {
;     ...
;     const float alpha = __builtin_amdgcn_exp2f(m - msafe);
;     m = mnew;
;     float rs0 = 0.f, rs1 = 0.f;
; #pragma unroll
;     for (int i = 0; i < 16; i += 2) { s[i] = __builtin_amdgcn_exp2f(s[i] * sc - msafe); s[i + 1] = __builtin_amdgcn_exp2f(s[i + 1] * sc - msafe); rs0 += s[i]; rs1 += s[i + 1]; }
;     l = l * alpha + (rs0 + rs1);
;     if (__builtin_amdgcn_ballot_w64(alpha != 1.0f) != 0ull) {
; #pragma unroll
;         for (int db = 0; db < 4; ++db) o[db] = o[db] * alpha; }
;     v4u pw0, pw1;
;     pw0.x = cvtpk(s[0], s[1]); pw0.y = cvtpk(s[2], s[3]); pw0.z = cvtpk(s[4], s[5]); pw0.w = cvtpk(s[6], s[7]);
;     pw1.x = cvtpk(s[8], s[9]); pw1.y = cvtpk(s[10], s[11]); pw1.z = cvtpk(s[12], s[13]); pw1.w = cvtpk(s[14], s[15]);
;     pf0 = __builtin_bit_cast(bf16x8, pw0); pf1 = __builtin_bit_cast(bf16x8, pw1);
; template <int NC>
; __device__ __forceinline__ void wg_attention128(LAS unsigned char* lds, const bf16* k1, int ldk1, const bf16* vt, int tok0, int nstages,
;         const bf16x8 (&qf)[NC], float sc, const CtlCausal& ctl, f32x16 (&o)[4], float& m, float& l, int tid, int r32, int hi) {
;     ...
;             ctl.mask(s, kvS + 32 * sb); att_softmax(s, sc, m, l, o, pa0, pa1);
;             __builtin_amdgcn_sched_barrier(0);
; #pragma unroll
;             for (int s_ = 0; s_ < 2; ++s_)
; #pragma unroll
;                 for (int db = 0; db < 4; ++db) o[db] = MFMA32(__builtin_bit_cast(bf16x8, av[s_ * 4 + db]), s_ ? pa1 : pa0, o[db]);
;             __builtin_amdgcn_sched_barrier(0);
.LBB0_146:
	v_fma_f32 v76, v245, s70, -v75
	v_fma_f32 v77, v240, s70, -v75
	v_exp_f32_e32 v76, v76
	v_exp_f32_e32 v77, v77
	v_fma_f32 v78, v238, s70, -v75
	v_fma_f32 v79, v235, s70, -v75
	v_exp_f32_e32 v78, v78
	v_exp_f32_e32 v79, v79
	v_fma_f32 v181, v234, s70, -v75
	v_fma_f32 v200, v233, s70, -v75
	v_exp_f32_e32 v181, v181
	v_exp_f32_e32 v200, v200
	v_fma_f32 v201, v232, s70, -v75
	v_fma_f32 v202, v231, s70, -v75
	v_exp_f32_e32 v201, v201
	v_exp_f32_e32 v202, v202
	v_fma_f32 v203, v230, s70, -v75
	v_fma_f32 v74, v74, s70, -v75
	v_add_f32_e32 v80, 0, v76
	v_add_f32_e32 v81, 0, v77
	v_exp_f32_e32 v203, v203
	v_exp_f32_e32 v74, v74
	v_add_f32_e32 v80, v78, v80
	v_add_f32_e32 v81, v79, v81
	v_add_f32_e32 v80, v181, v80
	v_add_f32_e32 v81, v200, v81
	v_fma_f32 v73, v73, s70, -v75
	v_fma_f32 v72, v72, s70, -v75
	v_add_f32_e32 v80, v201, v80
	v_add_f32_e32 v81, v202, v81
	v_exp_f32_e32 v208, v73
	v_exp_f32_e32 v209, v72
	v_fma_f32 v71, v71, s70, -v75
	v_fma_f32 v70, v70, s70, -v75
	v_add_f32_e32 v72, v203, v80
	v_add_f32_e32 v73, v74, v81
	v_exp_f32_e32 v80, v71
	v_exp_f32_e32 v81, v70
	v_fma_f32 v69, v69, s70, -v75
	v_fma_f32 v68, v68, s70, -v75
	v_exp_f32_e32 v69, v69
	v_exp_f32_e32 v210, v68
	v_add_f32_e32 v72, v208, v72
	v_add_f32_e32 v73, v209, v73
	v_add_f32_e32 v68, v80, v72
	v_add_f32_e32 v70, v81, v73
	v_add_f32_e32 v68, v69, v68
	v_add_f32_e32 v70, v210, v70
	v_add_f32_e32 v68, v68, v70
	v_fmac_f32_e32 v68, v227, v66
	v_cvt_pk_bf16_f32 v70, v76, v77
	v_cvt_pk_bf16_f32 v71, v78, v79
	v_cvt_pk_bf16_f32 v72, v181, v200
	v_cvt_pk_bf16_f32 v73, v201, v202
	v_cvt_pk_bf16_f32 v74, v203, v74
	v_cvt_pk_bf16_f32 v75, v208, v209
	v_cvt_pk_bf16_f32 v76, v80, v81
	v_cvt_pk_bf16_f32 v77, v69, v210
	v_cmp_neq_f32_e32 vcc, 1.0, v66
	s_cbranch_vccz .Lresc_skip_3
	v_pk_mul_f32 v[64:65], v[64:65], v[66:67] op_sel_hi:[1,0]
	v_pk_mul_f32 v[62:63], v[62:63], v[66:67] op_sel_hi:[1,0]
	v_pk_mul_f32 v[60:61], v[60:61], v[66:67] op_sel_hi:[1,0]
	v_pk_mul_f32 v[58:59], v[58:59], v[66:67] op_sel_hi:[1,0]
	v_pk_mul_f32 v[56:57], v[56:57], v[66:67] op_sel_hi:[1,0]
	v_pk_mul_f32 v[54:55], v[54:55], v[66:67] op_sel_hi:[1,0]
	v_pk_mul_f32 v[52:53], v[52:53], v[66:67] op_sel_hi:[1,0]
	v_pk_mul_f32 v[50:51], v[50:51], v[66:67] op_sel_hi:[1,0]
	v_pk_mul_f32 v[48:49], v[48:49], v[66:67] op_sel_hi:[1,0]
	v_pk_mul_f32 v[46:47], v[46:47], v[66:67] op_sel_hi:[1,0]
	v_pk_mul_f32 v[44:45], v[44:45], v[66:67] op_sel_hi:[1,0]
	v_pk_mul_f32 v[42:43], v[42:43], v[66:67] op_sel_hi:[1,0]
	v_pk_mul_f32 v[40:41], v[40:41], v[66:67] op_sel_hi:[1,0]
	v_pk_mul_f32 v[38:39], v[38:39], v[66:67] op_sel_hi:[1,0]
	v_pk_mul_f32 v[36:37], v[36:37], v[66:67] op_sel_hi:[1,0]
	v_pk_mul_f32 v[34:35], v[34:35], v[66:67] op_sel_hi:[1,0]
	v_pk_mul_f32 v[32:33], v[32:33], v[66:67] op_sel_hi:[1,0]
	v_pk_mul_f32 v[30:31], v[30:31], v[66:67] op_sel_hi:[1,0]
	v_pk_mul_f32 v[28:29], v[28:29], v[66:67] op_sel_hi:[1,0]
	v_pk_mul_f32 v[26:27], v[26:27], v[66:67] op_sel_hi:[1,0]
	v_pk_mul_f32 v[24:25], v[24:25], v[66:67] op_sel_hi:[1,0]
	v_pk_mul_f32 v[22:23], v[22:23], v[66:67] op_sel_hi:[1,0]
	v_pk_mul_f32 v[20:21], v[20:21], v[66:67] op_sel_hi:[1,0]
	v_pk_mul_f32 v[18:19], v[18:19], v[66:67] op_sel_hi:[1,0]
	v_pk_mul_f32 v[16:17], v[16:17], v[66:67] op_sel_hi:[1,0]
	v_pk_mul_f32 v[14:15], v[14:15], v[66:67] op_sel_hi:[1,0]
	v_pk_mul_f32 v[12:13], v[12:13], v[66:67] op_sel_hi:[1,0]
	v_pk_mul_f32 v[10:11], v[10:11], v[66:67] op_sel_hi:[1,0]
	v_pk_mul_f32 v[8:9], v[8:9], v[66:67] op_sel_hi:[1,0]
	v_pk_mul_f32 v[6:7], v[6:7], v[66:67] op_sel_hi:[1,0]
	v_pk_mul_f32 v[4:5], v[4:5], v[66:67] op_sel_hi:[1,0]
	v_pk_mul_f32 v[2:3], v[2:3], v[66:67] op_sel_hi:[1,0]
	s_nop 1
.Lresc_skip_3:
	s_waitcnt lgkmcnt(7)
	v_mfma_f32_32x32x16_bf16 v[50:65], v[162:165], v[70:73], v[50:65]
	s_waitcnt lgkmcnt(5)
	v_mfma_f32_32x32x16_bf16 v[34:49], v[166:169], v[70:73], v[34:49]
	s_waitcnt lgkmcnt(4)
	v_mfma_f32_32x32x16_bf16 v[18:33], v[174:177], v[70:73], v[18:33]
	s_waitcnt lgkmcnt(3)
	v_mfma_f32_32x32x16_bf16 v[2:17], v[170:173], v[70:73], v[2:17]
	v_mfma_f32_32x32x16_bf16 v[50:65], v[146:149], v[74:77], v[50:65]
	s_waitcnt lgkmcnt(2)
	v_mfma_f32_32x32x16_bf16 v[34:49], v[158:161], v[74:77], v[34:49]
	s_waitcnt lgkmcnt(1)
	v_mfma_f32_32x32x16_bf16 v[18:33], v[154:157], v[74:77], v[18:33]
	s_waitcnt lgkmcnt(0)
	v_mfma_f32_32x32x16_bf16 v[2:17], v[150:153], v[74:77], v[2:17]
	s_add_i32 s79, s79, -1
	s_add_i32 s88, s88, 32
	v_add_u32_e32 v228, 64, v228
	s_cmp_eq_u32 s79, 0
	v_add_u32_e32 v229, 0x2200, v229
	s_cbranch_scc1 .LBB0_148
	v_mov_b32_e32 v181, v67
	v_mov_b32_e32 v227, v68
	s_branch .LBB0_140

; #define MFMA32(a, b, c) __builtin_amdgcn_mfma_f32_32x32x16_bf16((a), (b), (c), 0, 0, 0)
; __device__ __forceinline__ void att_softmax(f32x16& s, float sc, float& m, float& l, f32x16 (&o)[4], bf16x8& pf0, bf16x8& pf1) {
;     ...
;     const float alpha = __builtin_amdgcn_exp2f(m - msafe);
;     m = mnew;
;     float rs0 = 0.f, rs1 = 0.f;
; #pragma unroll
;     for (int i = 0; i < 16; i += 2) { s[i] = __builtin_amdgcn_exp2f(s[i] * sc - msafe); s[i + 1] = __builtin_amdgcn_exp2f(s[i + 1] * sc - msafe); rs0 += s[i]; rs1 += s[i + 1]; }
;     l = l * alpha + (rs0 + rs1);
;     if (__builtin_amdgcn_ballot_w64(alpha != 1.0f) != 0ull) {
; #pragma unroll
;         for (int db = 0; db < 4; ++db) o[db] = o[db] * alpha; }
;     v4u pw0, pw1;
;     pw0.x = cvtpk(s[0], s[1]); pw0.y = cvtpk(s[2], s[3]); pw0.z = cvtpk(s[4], s[5]); pw0.w = cvtpk(s[6], s[7]);
;     pw1.x = cvtpk(s[8], s[9]); pw1.y = cvtpk(s[10], s[11]); pw1.z = cvtpk(s[12], s[13]); pw1.w = cvtpk(s[14], s[15]);
;     pf0 = __builtin_bit_cast(bf16x8, pw0); pf1 = __builtin_bit_cast(bf16x8, pw1);
; template <int NC>
; __device__ __forceinline__ void wg_attention128(LAS unsigned char* lds, const bf16* k1, int ldk1, const bf16* vt, int tok0, int nstages,
;         const bf16x8 (&qf)[NC], float sc, const CtlCausal& ctl, f32x16 (&o)[4], float& m, float& l, int tid, int r32, int hi) {
;     ...
;             ctl.mask(s, kvS + 32 * sb); att_softmax(s, sc, m, l, o, pa0, pa1);
;             __builtin_amdgcn_sched_barrier(0);
; #pragma unroll
;             for (int s_ = 0; s_ < 2; ++s_)
; #pragma unroll
;                 for (int db = 0; db < 4; ++db) o[db] = MFMA32(__builtin_bit_cast(bf16x8, av[s_ * 4 + db]), s_ ? pa1 : pa0, o[db]);
;             __builtin_amdgcn_sched_barrier(0);
.LBB0_278:
	v_fma_f32 v80, v80, s80, -v181
	v_exp_f32_e32 v136, v80
	v_fma_f32 v80, v81, s80, -v181
	v_exp_f32_e32 v81, v80
	v_fma_f32 v80, v82, s80, -v181
	v_exp_f32_e32 v137, v80
	v_fma_f32 v80, v83, s80, -v181
	v_exp_f32_e32 v83, v80
	v_fma_f32 v84, v84, s80, -v181
	v_fma_f32 v85, v85, s80, -v181
	v_exp_f32_e32 v84, v84
	v_exp_f32_e32 v85, v85
	v_fma_f32 v86, v86, s80, -v181
	v_fma_f32 v87, v87, s80, -v181
	v_exp_f32_e32 v86, v86
	v_exp_f32_e32 v87, v87
	v_fma_f32 v88, v88, s80, -v181
	v_fma_f32 v89, v89, s80, -v181
	v_exp_f32_e32 v88, v88
	v_exp_f32_e32 v89, v89
	v_fma_f32 v90, v90, s80, -v181
	v_fma_f32 v91, v91, s80, -v181
	v_add_f32_e32 v80, v137, v136
	v_add_f32_e32 v82, v83, v81
	v_exp_f32_e32 v90, v90
	v_exp_f32_e32 v91, v91
	v_fma_f32 v92, v92, s80, -v181
	v_fma_f32 v93, v93, s80, -v181
	v_add_f32_e32 v80, v84, v80
	v_add_f32_e32 v82, v85, v82
	v_exp_f32_e32 v92, v92
	v_exp_f32_e32 v93, v93
	v_fma_f32 v94, v94, s80, -v181
	v_fma_f32 v95, v95, s80, -v181
	v_add_f32_e32 v80, v86, v80
	v_add_f32_e32 v82, v87, v82
	v_exp_f32_e32 v94, v94
	v_exp_f32_e32 v95, v95
	v_add_f32_e32 v80, v88, v80
	v_add_f32_e32 v82, v89, v82
	v_add_f32_e32 v80, v90, v80
	v_add_f32_e32 v82, v91, v82
	v_add_f32_e32 v80, v92, v80
	v_add_f32_e32 v82, v93, v82
	v_add_f32_e32 v80, v94, v80
	v_add_f32_e32 v82, v95, v82
	v_add_f32_e32 v80, v80, v82
	v_fmac_f32_e32 v80, v219, v0
	v_cvt_pk_bf16_f32 v82, v136, v81
	v_cvt_pk_bf16_f32 v83, v137, v83
	v_cvt_pk_bf16_f32 v84, v84, v85
	v_cvt_pk_bf16_f32 v85, v86, v87
	v_cvt_pk_bf16_f32 v86, v88, v89
	v_cvt_pk_bf16_f32 v87, v90, v91
	v_cvt_pk_bf16_f32 v88, v92, v93
	v_cvt_pk_bf16_f32 v89, v94, v95
	v_cmp_neq_f32_e32 vcc, 1.0, v0
	s_cbranch_vccz .Lresc_skip_4
	v_pk_mul_f32 v[78:79], v[0:1], v[78:79] op_sel_hi:[0,1]
	v_pk_mul_f32 v[76:77], v[0:1], v[76:77] op_sel_hi:[0,1]
	v_pk_mul_f32 v[74:75], v[0:1], v[74:75] op_sel_hi:[0,1]
	v_pk_mul_f32 v[72:73], v[0:1], v[72:73] op_sel_hi:[0,1]
	v_pk_mul_f32 v[70:71], v[0:1], v[70:71] op_sel_hi:[0,1]
	v_pk_mul_f32 v[68:69], v[0:1], v[68:69] op_sel_hi:[0,1]
	v_pk_mul_f32 v[66:67], v[0:1], v[66:67] op_sel_hi:[0,1]
	v_pk_mul_f32 v[64:65], v[0:1], v[64:65] op_sel_hi:[0,1]
	v_pk_mul_f32 v[62:63], v[0:1], v[62:63] op_sel_hi:[0,1]
	v_pk_mul_f32 v[60:61], v[0:1], v[60:61] op_sel_hi:[0,1]
	v_pk_mul_f32 v[58:59], v[0:1], v[58:59] op_sel_hi:[0,1]
	v_pk_mul_f32 v[56:57], v[0:1], v[56:57] op_sel_hi:[0,1]
	v_pk_mul_f32 v[54:55], v[0:1], v[54:55] op_sel_hi:[0,1]
	v_pk_mul_f32 v[52:53], v[0:1], v[52:53] op_sel_hi:[0,1]
	v_pk_mul_f32 v[50:51], v[0:1], v[50:51] op_sel_hi:[0,1]
	v_pk_mul_f32 v[48:49], v[0:1], v[48:49] op_sel_hi:[0,1]
	v_pk_mul_f32 v[46:47], v[0:1], v[46:47] op_sel_hi:[0,1]
	v_pk_mul_f32 v[44:45], v[0:1], v[44:45] op_sel_hi:[0,1]
	v_pk_mul_f32 v[42:43], v[0:1], v[42:43] op_sel_hi:[0,1]
	v_pk_mul_f32 v[40:41], v[0:1], v[40:41] op_sel_hi:[0,1]
	v_pk_mul_f32 v[38:39], v[0:1], v[38:39] op_sel_hi:[0,1]
	v_pk_mul_f32 v[36:37], v[0:1], v[36:37] op_sel_hi:[0,1]
	v_pk_mul_f32 v[34:35], v[0:1], v[34:35] op_sel_hi:[0,1]
	v_pk_mul_f32 v[32:33], v[0:1], v[32:33] op_sel_hi:[0,1]
	v_pk_mul_f32 v[30:31], v[0:1], v[30:31] op_sel_hi:[0,1]
	v_pk_mul_f32 v[28:29], v[0:1], v[28:29] op_sel_hi:[0,1]
	v_pk_mul_f32 v[26:27], v[0:1], v[26:27] op_sel_hi:[0,1]
	v_pk_mul_f32 v[24:25], v[0:1], v[24:25] op_sel_hi:[0,1]
	v_pk_mul_f32 v[22:23], v[0:1], v[22:23] op_sel_hi:[0,1]
	v_pk_mul_f32 v[20:21], v[0:1], v[20:21] op_sel_hi:[0,1]
	v_pk_mul_f32 v[18:19], v[0:1], v[18:19] op_sel_hi:[0,1]
	v_pk_mul_f32 v[16:17], v[0:1], v[16:17] op_sel_hi:[0,1]
	s_nop 1
.Lresc_skip_4:
	s_waitcnt lgkmcnt(11)
	v_mfma_f32_32x32x16_bf16 v[64:79], v[152:155], v[82:85], v[64:79]
	s_waitcnt lgkmcnt(9)
	v_mfma_f32_32x32x16_bf16 v[48:63], v[160:163], v[82:85], v[48:63]
	s_waitcnt lgkmcnt(8)
	v_mfma_f32_32x32x16_bf16 v[32:47], v[168:171], v[82:85], v[32:47]
	s_waitcnt lgkmcnt(7)
	v_mfma_f32_32x32x16_bf16 v[16:31], v[164:167], v[82:85], v[16:31]
	v_mfma_f32_32x32x16_bf16 v[64:79], v[140:143], v[86:89], v[64:79]
	s_waitcnt lgkmcnt(6)
	v_mfma_f32_32x32x16_bf16 v[48:63], v[148:151], v[86:89], v[48:63]
	s_waitcnt lgkmcnt(5)
	v_mfma_f32_32x32x16_bf16 v[32:47], v[144:147], v[86:89], v[32:47]
	s_waitcnt lgkmcnt(4)
	v_mfma_f32_32x32x16_bf16 v[16:31], v[156:159], v[86:89], v[16:31]
	s_sub_i32 s67, s67, 32
	s_cmp_eq_u32 s61, s43
	v_add_u32_e32 v15, 64, v15
	s_cbranch_scc1 .LBB0_281
	v_mov_b32_e32 v219, v80
	v_mov_b32_e32 v240, v221
	s_mov_b32 s61, s62
	s_branch .LBB0_272

; #define MFMA32(a, b, c) __builtin_amdgcn_mfma_f32_32x32x16_bf16((a), (b), (c), 0, 0, 0)
; __device__ __forceinline__ void att_softmax(f32x16& s, float sc, float& m, float& l, f32x16 (&o)[4], bf16x8& pf0, bf16x8& pf1) {
;     ...
;     const float alpha = __builtin_amdgcn_exp2f(m - msafe);
;     m = mnew;
;     float rs0 = 0.f, rs1 = 0.f;
; #pragma unroll
;     for (int i = 0; i < 16; i += 2) { s[i] = __builtin_amdgcn_exp2f(s[i] * sc - msafe); s[i + 1] = __builtin_amdgcn_exp2f(s[i + 1] * sc - msafe); rs0 += s[i]; rs1 += s[i + 1]; }
;     l = l * alpha + (rs0 + rs1);
;     if (__builtin_amdgcn_ballot_w64(alpha != 1.0f) != 0ull) {
; #pragma unroll
;         for (int db = 0; db < 4; ++db) o[db] = o[db] * alpha; }
;     v4u pw0, pw1;
;     pw0.x = cvtpk(s[0], s[1]); pw0.y = cvtpk(s[2], s[3]); pw0.z = cvtpk(s[4], s[5]); pw0.w = cvtpk(s[6], s[7]);
;     pw1.x = cvtpk(s[8], s[9]); pw1.y = cvtpk(s[10], s[11]); pw1.z = cvtpk(s[12], s[13]); pw1.w = cvtpk(s[14], s[15]);
;     pf0 = __builtin_bit_cast(bf16x8, pw0); pf1 = __builtin_bit_cast(bf16x8, pw1);
; template <int NC1, int NC2, class Ctl> ...
;     ...
;                 ctl.mask(s, sb ? kvB : kvA); att_softmax(s, sc, m, l, o, pa0, pa1);
;                 __builtin_amdgcn_sched_barrier(0);
; #pragma unroll
;                 for (int s_ = 0; s_ < 2; ++s_)
; #pragma unroll
;                     for (int db = 0; db < 4; ++db) o[db] = MFMA32(__builtin_bit_cast(bf16x8, av[s_ * 4 + db]), s_ ? pa1 : pa0, o[db]);
.LBB0_304:
	v_fma_f32 v80, v80, s70, -v240
	v_fma_f32 v81, v81, s70, -v240
	v_exp_f32_e32 v80, v80
	v_exp_f32_e32 v81, v81
	v_fma_f32 v82, v82, s70, -v240
	v_fma_f32 v83, v83, s70, -v240
	v_exp_f32_e32 v82, v82
	v_exp_f32_e32 v83, v83
	v_fma_f32 v84, v84, s70, -v240
	v_fma_f32 v85, v85, s70, -v240
	v_exp_f32_e32 v84, v84
	v_exp_f32_e32 v85, v85
	v_fma_f32 v86, v86, s70, -v240
	v_fma_f32 v87, v87, s70, -v240
	v_exp_f32_e32 v86, v86
	v_exp_f32_e32 v87, v87
	v_fma_f32 v88, v88, s70, -v240
	v_fma_f32 v89, v89, s70, -v240
	v_exp_f32_e32 v88, v88
	v_exp_f32_e32 v89, v89
	v_fma_f32 v90, v90, s70, -v240
	v_fma_f32 v91, v91, s70, -v240
	v_add_f32_e32 v200, v82, v80
	v_add_f32_e32 v201, v83, v81
	v_exp_f32_e32 v90, v90
	v_exp_f32_e32 v91, v91
	v_fma_f32 v92, v92, s70, -v240
	v_fma_f32 v93, v93, s70, -v240
	v_add_f32_e32 v200, v84, v200
	v_add_f32_e32 v201, v85, v201
	v_exp_f32_e32 v92, v92
	v_exp_f32_e32 v93, v93
	v_fma_f32 v94, v94, s70, -v240
	v_fma_f32 v95, v95, s70, -v240
	v_add_f32_e32 v200, v86, v200
	v_add_f32_e32 v201, v87, v201
	v_exp_f32_e32 v94, v94
	v_exp_f32_e32 v95, v95
	v_add_f32_e32 v200, v88, v200
	v_add_f32_e32 v201, v89, v201
	v_add_f32_e32 v200, v90, v200
	v_add_f32_e32 v201, v91, v201
	v_add_f32_e32 v200, v92, v200
	v_add_f32_e32 v201, v93, v201
	v_add_f32_e32 v200, v94, v200
	v_add_f32_e32 v201, v95, v201
	v_add_f32_e32 v200, v200, v201
	v_fmac_f32_e32 v200, v227, v0
	v_cvt_pk_bf16_f32 v80, v80, v81
	v_cvt_pk_bf16_f32 v81, v82, v83
	v_cvt_pk_bf16_f32 v82, v84, v85
	v_cvt_pk_bf16_f32 v83, v86, v87
	v_cvt_pk_bf16_f32 v84, v88, v89
	v_cvt_pk_bf16_f32 v85, v90, v91
	v_cvt_pk_bf16_f32 v86, v92, v93
	v_cvt_pk_bf16_f32 v87, v94, v95
	v_cmp_neq_f32_e32 vcc, 1.0, v0
	s_cbranch_vccz .Lresc_skip_5
	v_pk_mul_f32 v[78:79], v[78:79], v[0:1] op_sel_hi:[1,0]
	v_pk_mul_f32 v[76:77], v[76:77], v[0:1] op_sel_hi:[1,0]
	v_pk_mul_f32 v[74:75], v[74:75], v[0:1] op_sel_hi:[1,0]
	v_pk_mul_f32 v[72:73], v[72:73], v[0:1] op_sel_hi:[1,0]
	v_pk_mul_f32 v[70:71], v[70:71], v[0:1] op_sel_hi:[1,0]
	v_pk_mul_f32 v[68:69], v[68:69], v[0:1] op_sel_hi:[1,0]
	v_pk_mul_f32 v[66:67], v[66:67], v[0:1] op_sel_hi:[1,0]
	v_pk_mul_f32 v[64:65], v[64:65], v[0:1] op_sel_hi:[1,0]
	v_pk_mul_f32 v[62:63], v[62:63], v[0:1] op_sel_hi:[1,0]
	v_pk_mul_f32 v[60:61], v[60:61], v[0:1] op_sel_hi:[1,0]
	v_pk_mul_f32 v[58:59], v[58:59], v[0:1] op_sel_hi:[1,0]
	v_pk_mul_f32 v[56:57], v[56:57], v[0:1] op_sel_hi:[1,0]
	v_pk_mul_f32 v[54:55], v[54:55], v[0:1] op_sel_hi:[1,0]
	v_pk_mul_f32 v[52:53], v[52:53], v[0:1] op_sel_hi:[1,0]
	v_pk_mul_f32 v[50:51], v[50:51], v[0:1] op_sel_hi:[1,0]
	v_pk_mul_f32 v[48:49], v[48:49], v[0:1] op_sel_hi:[1,0]
	v_pk_mul_f32 v[46:47], v[46:47], v[0:1] op_sel_hi:[1,0]
	v_pk_mul_f32 v[44:45], v[44:45], v[0:1] op_sel_hi:[1,0]
	v_pk_mul_f32 v[42:43], v[42:43], v[0:1] op_sel_hi:[1,0]
	v_pk_mul_f32 v[40:41], v[40:41], v[0:1] op_sel_hi:[1,0]
	v_pk_mul_f32 v[38:39], v[38:39], v[0:1] op_sel_hi:[1,0]
	v_pk_mul_f32 v[36:37], v[36:37], v[0:1] op_sel_hi:[1,0]
	v_pk_mul_f32 v[34:35], v[34:35], v[0:1] op_sel_hi:[1,0]
	v_pk_mul_f32 v[32:33], v[32:33], v[0:1] op_sel_hi:[1,0]
	v_pk_mul_f32 v[30:31], v[30:31], v[0:1] op_sel_hi:[1,0]
	v_pk_mul_f32 v[28:29], v[28:29], v[0:1] op_sel_hi:[1,0]
	v_pk_mul_f32 v[26:27], v[26:27], v[0:1] op_sel_hi:[1,0]
	v_pk_mul_f32 v[24:25], v[24:25], v[0:1] op_sel_hi:[1,0]
	v_pk_mul_f32 v[22:23], v[22:23], v[0:1] op_sel_hi:[1,0]
	v_pk_mul_f32 v[20:21], v[20:21], v[0:1] op_sel_hi:[1,0]
	v_pk_mul_f32 v[18:19], v[18:19], v[0:1] op_sel_hi:[1,0]
	v_pk_mul_f32 v[16:17], v[16:17], v[0:1] op_sel_hi:[1,0]
	s_nop 1
.Lresc_skip_5:
	s_waitcnt lgkmcnt(7)
	v_mfma_f32_32x32x16_bf16 v[64:79], v[184:187], v[80:83], v[64:79]
	s_waitcnt lgkmcnt(5)
	v_mfma_f32_32x32x16_bf16 v[48:63], v[192:195], v[80:83], v[48:63]
	s_waitcnt lgkmcnt(4)
	v_mfma_f32_32x32x16_bf16 v[32:47], v[188:191], v[80:83], v[32:47]
	s_waitcnt lgkmcnt(3)
	v_mfma_f32_32x32x16_bf16 v[16:31], v[180:183], v[80:83], v[16:31]
	v_mfma_f32_32x32x16_bf16 v[64:79], v[164:167], v[84:87], v[64:79]
	s_waitcnt lgkmcnt(2)
	v_mfma_f32_32x32x16_bf16 v[48:63], v[176:179], v[84:87], v[48:63]
	s_waitcnt lgkmcnt(1)
	v_mfma_f32_32x32x16_bf16 v[32:47], v[172:175], v[84:87], v[32:47]
	s_waitcnt lgkmcnt(0)
	v_mfma_f32_32x32x16_bf16 v[16:31], v[168:171], v[84:87], v[16:31]
	v_mov_b32_e32 v227, v200
	s_and_b64 vcc, exec, s[6:7]
	s_cbranch_vccz .LBB0_311

; #define MFMA32(a, b, c) __builtin_amdgcn_mfma_f32_32x32x16_bf16((a), (b), (c), 0, 0, 0)
; __device__ __forceinline__ void att_softmax(f32x16& s, float sc, float& m, float& l, f32x16 (&o)[4], bf16x8& pf0, bf16x8& pf1) {
;     ...
;     const float alpha = __builtin_amdgcn_exp2f(m - msafe);
;     m = mnew;
;     float rs0 = 0.f, rs1 = 0.f;
; #pragma unroll
;     for (int i = 0; i < 16; i += 2) { s[i] = __builtin_amdgcn_exp2f(s[i] * sc - msafe); s[i + 1] = __builtin_amdgcn_exp2f(s[i + 1] * sc - msafe); rs0 += s[i]; rs1 += s[i + 1]; }
;     l = l * alpha + (rs0 + rs1);
;     if (__builtin_amdgcn_ballot_w64(alpha != 1.0f) != 0ull) {
; #pragma unroll
;         for (int db = 0; db < 4; ++db) o[db] = o[db] * alpha; }
;     v4u pw0, pw1;
;     pw0.x = cvtpk(s[0], s[1]); pw0.y = cvtpk(s[2], s[3]); pw0.z = cvtpk(s[4], s[5]); pw0.w = cvtpk(s[6], s[7]);
;     pw1.x = cvtpk(s[8], s[9]); pw1.y = cvtpk(s[10], s[11]); pw1.z = cvtpk(s[12], s[13]); pw1.w = cvtpk(s[14], s[15]);
;     pf0 = __builtin_bit_cast(bf16x8, pw0); pf1 = __builtin_bit_cast(bf16x8, pw1);
; template <int NC1, int NC2, class Ctl> ...
;     ...
;                 ctl.mask(s, sb ? kvB : kvA); att_softmax(s, sc, m, l, o, pa0, pa1);
;                 __builtin_amdgcn_sched_barrier(0);
; #pragma unroll
;                 for (int s_ = 0; s_ < 2; ++s_)
; #pragma unroll
;                     for (int db = 0; db < 4; ++db) o[db] = MFMA32(__builtin_bit_cast(bf16x8, av[s_ * 4 + db]), s_ ? pa1 : pa0, o[db]);
.LBB0_313:
	v_fma_f32 v15, v15, s70, -v95
	v_fma_f32 v80, v80, s70, -v95
	v_exp_f32_e32 v15, v15
	v_exp_f32_e32 v80, v80
	v_fma_f32 v81, v81, s70, -v95
	v_fma_f32 v82, v82, s70, -v95
	v_exp_f32_e32 v81, v81
	v_exp_f32_e32 v82, v82
	v_fma_f32 v83, v83, s70, -v95
	v_fma_f32 v84, v84, s70, -v95
	v_exp_f32_e32 v83, v83
	v_exp_f32_e32 v84, v84
	v_fma_f32 v85, v85, s70, -v95
	v_fma_f32 v86, v86, s70, -v95
	v_exp_f32_e32 v85, v85
	v_exp_f32_e32 v86, v86
	v_fma_f32 v87, v87, s70, -v95
	v_fma_f32 v88, v88, s70, -v95
	v_exp_f32_e32 v87, v87
	v_exp_f32_e32 v88, v88
	v_fma_f32 v89, v89, s70, -v95
	v_fma_f32 v90, v90, s70, -v95
	v_add_f32_e32 v132, v81, v15
	v_add_f32_e32 v133, v82, v80
	v_exp_f32_e32 v89, v89
	v_exp_f32_e32 v90, v90
	v_fma_f32 v91, v91, s70, -v95
	v_fma_f32 v92, v92, s70, -v95
	v_add_f32_e32 v132, v83, v132
	v_add_f32_e32 v133, v84, v133
	v_exp_f32_e32 v91, v91
	v_exp_f32_e32 v92, v92
	v_fma_f32 v93, v93, s70, -v95
	v_fma_f32 v94, v94, s70, -v95
	v_add_f32_e32 v132, v85, v132
	v_add_f32_e32 v133, v86, v133
	v_exp_f32_e32 v93, v93
	v_exp_f32_e32 v94, v94
	v_add_f32_e32 v132, v87, v132
	v_add_f32_e32 v133, v88, v133
	v_add_f32_e32 v132, v89, v132
	v_add_f32_e32 v133, v90, v133
	v_add_f32_e32 v95, v91, v132
	v_add_f32_e32 v132, v92, v133
	v_add_f32_e32 v95, v93, v95
	v_add_f32_e32 v132, v94, v132
	v_add_f32_e32 v95, v95, v132
	v_fmac_f32_e32 v95, v227, v0
	v_cvt_pk_bf16_f32 v80, v15, v80
	v_cvt_pk_bf16_f32 v81, v81, v82
	v_cvt_pk_bf16_f32 v82, v83, v84
	v_cvt_pk_bf16_f32 v83, v85, v86
	v_cvt_pk_bf16_f32 v84, v87, v88
	v_cvt_pk_bf16_f32 v85, v89, v90
	v_cvt_pk_bf16_f32 v86, v91, v92
	v_cvt_pk_bf16_f32 v87, v93, v94
	v_cmp_neq_f32_e32 vcc, 1.0, v0
	s_cbranch_vccz .Lresc_skip_6
	v_pk_mul_f32 v[78:79], v[78:79], v[0:1] op_sel_hi:[1,0]
	v_pk_mul_f32 v[76:77], v[76:77], v[0:1] op_sel_hi:[1,0]
	v_pk_mul_f32 v[74:75], v[74:75], v[0:1] op_sel_hi:[1,0]
	v_pk_mul_f32 v[72:73], v[72:73], v[0:1] op_sel_hi:[1,0]
	v_pk_mul_f32 v[70:71], v[70:71], v[0:1] op_sel_hi:[1,0]
	v_pk_mul_f32 v[68:69], v[68:69], v[0:1] op_sel_hi:[1,0]
	v_pk_mul_f32 v[66:67], v[66:67], v[0:1] op_sel_hi:[1,0]
	v_pk_mul_f32 v[64:65], v[64:65], v[0:1] op_sel_hi:[1,0]
	v_pk_mul_f32 v[62:63], v[62:63], v[0:1] op_sel_hi:[1,0]
	v_pk_mul_f32 v[60:61], v[60:61], v[0:1] op_sel_hi:[1,0]
	v_pk_mul_f32 v[58:59], v[58:59], v[0:1] op_sel_hi:[1,0]
	v_pk_mul_f32 v[56:57], v[56:57], v[0:1] op_sel_hi:[1,0]
	v_pk_mul_f32 v[54:55], v[54:55], v[0:1] op_sel_hi:[1,0]
	v_pk_mul_f32 v[52:53], v[52:53], v[0:1] op_sel_hi:[1,0]
	v_pk_mul_f32 v[50:51], v[50:51], v[0:1] op_sel_hi:[1,0]
	v_pk_mul_f32 v[48:49], v[48:49], v[0:1] op_sel_hi:[1,0]
	v_pk_mul_f32 v[46:47], v[46:47], v[0:1] op_sel_hi:[1,0]
	v_pk_mul_f32 v[44:45], v[44:45], v[0:1] op_sel_hi:[1,0]
	v_pk_mul_f32 v[42:43], v[42:43], v[0:1] op_sel_hi:[1,0]
	v_pk_mul_f32 v[40:41], v[40:41], v[0:1] op_sel_hi:[1,0]
	v_pk_mul_f32 v[38:39], v[38:39], v[0:1] op_sel_hi:[1,0]
	v_pk_mul_f32 v[36:37], v[36:37], v[0:1] op_sel_hi:[1,0]
	v_pk_mul_f32 v[34:35], v[34:35], v[0:1] op_sel_hi:[1,0]
	v_pk_mul_f32 v[32:33], v[32:33], v[0:1] op_sel_hi:[1,0]
	v_pk_mul_f32 v[30:31], v[30:31], v[0:1] op_sel_hi:[1,0]
	v_pk_mul_f32 v[28:29], v[28:29], v[0:1] op_sel_hi:[1,0]
	v_pk_mul_f32 v[26:27], v[26:27], v[0:1] op_sel_hi:[1,0]
	v_pk_mul_f32 v[24:25], v[24:25], v[0:1] op_sel_hi:[1,0]
	v_pk_mul_f32 v[22:23], v[22:23], v[0:1] op_sel_hi:[1,0]
	v_pk_mul_f32 v[20:21], v[20:21], v[0:1] op_sel_hi:[1,0]
	v_pk_mul_f32 v[18:19], v[18:19], v[0:1] op_sel_hi:[1,0]
	v_pk_mul_f32 v[16:17], v[16:17], v[0:1] op_sel_hi:[1,0]
	s_nop 1
.Lresc_skip_6:
	s_waitcnt lgkmcnt(7)
	v_mfma_f32_32x32x16_bf16 v[64:79], v[156:159], v[80:83], v[64:79]
	s_waitcnt lgkmcnt(5)
	v_mfma_f32_32x32x16_bf16 v[48:63], v[164:167], v[80:83], v[48:63]
	s_waitcnt lgkmcnt(4)
	v_mfma_f32_32x32x16_bf16 v[32:47], v[160:163], v[80:83], v[32:47]
	s_waitcnt lgkmcnt(3)
	v_mfma_f32_32x32x16_bf16 v[16:31], v[152:155], v[80:83], v[16:31]
	v_mfma_f32_32x32x16_bf16 v[64:79], v[140:143], v[84:87], v[64:79]
	s_waitcnt lgkmcnt(2)
	v_mfma_f32_32x32x16_bf16 v[48:63], v[148:151], v[84:87], v[48:63]
	s_waitcnt lgkmcnt(1)
	v_mfma_f32_32x32x16_bf16 v[32:47], v[144:147], v[84:87], v[32:47]
	s_waitcnt lgkmcnt(0)
	v_mfma_f32_32x32x16_bf16 v[16:31], v[136:139], v[84:87], v[16:31]
	v_mov_b32_e32 v227, v95
	s_andn2_b64 vcc, exec, s[14:15]
	s_cbranch_vccz .LBB0_307
	s_branch .LBB0_308
